# pass 1: workgroups 192..255 do three transpose items before P1 (no idle wait for the adaLN counter)
# speedup vs baseline: 1.0019x; 1.0011x over previous
.LBB0_15:
	s_add_i32 s26, s26, s6
	s_add_i32 s7, s7, s10
	s_add_i32 s11, s11, s24
	s_cmp_lg_u32 s100, 0
	s_cbranch_scc1 .Lp0_pass2
	s_cmpk_lt_i32 s26, 0xc00
	s_cbranch_scc1 .LBB0_16
	s_cmpk_lt_u32 s4, 0x600
	s_cbranch_scc1 .Lp0_p1exit
	s_cmpk_lt_i32 s26, 0x1c00
	s_cbranch_scc1 .LBB0_16
.Lp0_p1exit:
	s_mov_b32 s101, s26
	s_branch .LBB0_36
